# w_out residual phase: K loop touches the unit's f32 residual tile (one dword load per lane per iteration, 64 B granules) so the epilogue residual reads hit cache
# baseline (speedup 1.0000x reference)
; #define PG8_STAGE(bufoff, gbase, voff) do { _Pragma("unroll") for (int _i = 0; _i < 2; ++_i) \
;     __builtin_amdgcn_global_load_lds((const unsigned*)((const char*)(gbase) + (voff)[_i]), (LAS unsigned*)(lds + (bufoff) + ldsw + _i * 8192), 16, 0, 0); } while (0)
; #define PG8_WAIT_V(n) asm volatile("s_waitcnt vmcnt(" #n ")" ::: "memory")
; #define PG8_BAR __builtin_amdgcn_s_barrier()
; template <class Epi, class Sched>
; DI void gemm_phase(LAS unsigned char* lds, const Gemm g, const Sched& S, const Epi& E) {
;     ...
;   f32x4 acc[2][2][4][2];
; #pragma unroll
;   for (int a = 0; a < 2; ++a)
; #pragma unroll
;     for (int b = 0; b < 2; ++b)
; #pragma unroll
;       for (int m = 0; m < 4; ++m)
; #pragma unroll
;         for (int n = 0; n < 2; ++n) acc[a][b][m][n] = (f32x4){0.f, 0.f, 0.f, 0.f};
;     ...
;   PG8_WAIT_V(4); PG8_BAR;
;   PG8_STAGE(PG8_SB(1, 0), cB + kstep, voffB); PG8_STAGE(PG8_SA(1, 0), cA + kstep, voffA); PG8_STAGE(PG8_SB(1, 1), cB + hstepB + kstep, voffB);
;   PG8_WAIT_V(6); PG8_BAR;
.LBB0_215:
	v_lshl_add_u64 v[4:5], s[12:13], 0, v[0:1]
	v_mov_b32_e32 v131, v1
	v_lshl_add_u64 v[6:7], s[12:13], 0, v[130:131]
	v_and_b32_e32 v132, 15, v2
	v_bfe_u32 v136, v2, 4, 2
	s_add_i32 m0, s30, 0x18000
	v_lshl_add_u64 v[2:3], v[4:5], 0, s[70:71]
	v_lshl_add_u64 v[8:9], s[14:15], 0, v[0:1]
	s_waitcnt vmcnt(4)
	s_barrier
	global_load_lds_dwordx4 v[2:3], off
	v_lshl_add_u64 v[2:3], v[6:7], 0, s[70:71]
	s_add_i32 m0, s30, 0x1a000
	s_add_i32 s36, s30, 0x8000
	v_lshl_add_u64 v[10:11], s[14:15], 0, v[130:131]
	global_load_lds_dwordx4 v[2:3], off
	v_lshl_add_u64 v[2:3], v[8:9], 0, s[70:71]
	s_mov_b32 m0, s36
	s_add_i32 s37, s30, 0xa000
	v_lshl_add_u64 v[12:13], s[18:19], 0, v[0:1]
	global_load_lds_dwordx4 v[2:3], off
	v_lshl_add_u64 v[2:3], v[10:11], 0, s[70:71]
	s_mov_b32 m0, s37
	v_lshl_add_u64 v[14:15], s[18:19], 0, v[130:131]
	global_load_lds_dwordx4 v[2:3], off
	s_add_i32 m0, s30, 0x1c000
	v_lshl_add_u64 v[2:3], v[12:13], 0, s[70:71]
	global_load_lds_dwordx4 v[2:3], off
	v_lshl_add_u64 v[2:3], v[14:15], 0, s[70:71]
	s_add_i32 m0, s30, 0x1e000
	s_lshl_b32 s18, s21, 5
	global_load_lds_dwordx4 v[2:3], off
	s_waitcnt vmcnt(6)
	s_and_b32 s27, s18, 0x60
	v_mov_b32_e32 v129, 0
	v_lshl_or_b32 v146, s20, 6, v132
	s_cmp_lt_i32 s16, 64
	v_mov_b32_e32 v128, v129
	v_mov_b32_e32 v127, v129
	v_mov_b32_e32 v126, v129
	v_mov_b32_e32 v125, v129
	v_mov_b32_e32 v124, v129
	v_mov_b32_e32 v123, v129
	v_mov_b32_e32 v122, v129
	v_mov_b32_e32 v113, v129
	v_mov_b32_e32 v112, v129
	v_mov_b32_e32 v111, v129
	v_mov_b32_e32 v110, v129
	v_mov_b32_e32 v109, v129
	v_mov_b32_e32 v108, v129
	v_mov_b32_e32 v107, v129
	v_mov_b32_e32 v106, v129
	v_mov_b32_e32 v97, v129
	v_mov_b32_e32 v96, v129
	v_mov_b32_e32 v95, v129
	v_mov_b32_e32 v94, v129
	v_mov_b32_e32 v93, v129
	v_mov_b32_e32 v92, v129
	v_mov_b32_e32 v91, v129
	v_mov_b32_e32 v90, v129
	v_mov_b32_e32 v81, v129
	v_mov_b32_e32 v80, v129
	v_mov_b32_e32 v79, v129
	v_mov_b32_e32 v78, v129
	v_mov_b32_e32 v77, v129
	v_mov_b32_e32 v76, v129
	v_mov_b32_e32 v75, v129
	v_mov_b32_e32 v74, v129
	v_mov_b32_e32 v121, v129
	v_mov_b32_e32 v120, v129
	v_mov_b32_e32 v119, v129
	v_mov_b32_e32 v118, v129
	v_mov_b32_e32 v117, v129
	v_mov_b32_e32 v116, v129
	v_mov_b32_e32 v115, v129
	v_mov_b32_e32 v114, v129
	v_mov_b32_e32 v105, v129
	v_mov_b32_e32 v104, v129
	v_mov_b32_e32 v103, v129
	v_mov_b32_e32 v102, v129
	v_mov_b32_e32 v101, v129
	v_mov_b32_e32 v100, v129
	v_mov_b32_e32 v99, v129
	v_mov_b32_e32 v98, v129
	v_mov_b32_e32 v89, v129
	v_mov_b32_e32 v88, v129
	v_mov_b32_e32 v87, v129
	v_mov_b32_e32 v86, v129
	v_mov_b32_e32 v85, v129
	v_mov_b32_e32 v84, v129
	v_mov_b32_e32 v83, v129
	v_mov_b32_e32 v82, v129
	v_mov_b32_e32 v73, v129
	v_mov_b32_e32 v72, v129
	v_mov_b32_e32 v71, v129
	v_mov_b32_e32 v70, v129
	v_mov_b32_e32 v69, v129
	v_mov_b32_e32 v68, v129
	v_mov_b32_e32 v67, v129
	v_mov_b32_e32 v66, v129
	v_mov_b32_e32 v65, v129
	v_mov_b32_e32 v64, v129
	v_mov_b32_e32 v63, v129
	v_mov_b32_e32 v62, v129
	v_mov_b32_e32 v61, v129
	v_mov_b32_e32 v60, v129
	v_mov_b32_e32 v59, v129
	v_mov_b32_e32 v58, v129
	v_mov_b32_e32 v53, v129
	v_mov_b32_e32 v52, v129
	v_mov_b32_e32 v51, v129
	v_mov_b32_e32 v50, v129
	v_mov_b32_e32 v45, v129
	v_mov_b32_e32 v44, v129
	v_mov_b32_e32 v43, v129
	v_mov_b32_e32 v42, v129
	v_mov_b32_e32 v37, v129
	v_mov_b32_e32 v36, v129
	v_mov_b32_e32 v35, v129
	v_mov_b32_e32 v34, v129
	v_mov_b32_e32 v29, v129
	v_mov_b32_e32 v28, v129
	v_mov_b32_e32 v27, v129
	v_mov_b32_e32 v26, v129
	v_mov_b32_e32 v17, v129
	v_mov_b32_e32 v16, v129
	v_mov_b32_e32 v15, v129
	v_mov_b32_e32 v14, v129
	v_mov_b32_e32 v13, v129
	v_mov_b32_e32 v12, v129
	v_mov_b32_e32 v11, v129
	v_mov_b32_e32 v10, v129
	v_mov_b32_e32 v57, v129
	v_mov_b32_e32 v56, v129
	v_mov_b32_e32 v55, v129
	v_mov_b32_e32 v54, v129
	v_mov_b32_e32 v49, v129
	v_mov_b32_e32 v48, v129
	v_mov_b32_e32 v47, v129
	v_mov_b32_e32 v46, v129
	v_mov_b32_e32 v41, v129
	v_mov_b32_e32 v40, v129
	v_mov_b32_e32 v39, v129
	v_mov_b32_e32 v38, v129
	v_mov_b32_e32 v33, v129
	v_mov_b32_e32 v32, v129
	v_mov_b32_e32 v31, v129
	v_mov_b32_e32 v30, v129
	v_mov_b32_e32 v25, v129
	v_mov_b32_e32 v24, v129
	v_mov_b32_e32 v23, v129
	v_mov_b32_e32 v22, v129
	v_mov_b32_e32 v21, v129
	v_mov_b32_e32 v20, v129
	v_mov_b32_e32 v19, v129
	v_mov_b32_e32 v18, v129
	v_mov_b32_e32 v9, v129
	v_mov_b32_e32 v8, v129
	v_mov_b32_e32 v7, v129
	v_mov_b32_e32 v6, v129
	v_mov_b32_e32 v5, v129
	v_mov_b32_e32 v4, v129
	v_mov_b32_e32 v3, v129
	v_mov_b32_e32 v2, v129
	s_barrier
	s_cbranch_scc1 .LBB0_218
; #define PG8_STAGE(bufoff, gbase, voff) do { _Pragma("unroll") for (int _i = 0; _i < 2; ++_i) \
;     __builtin_amdgcn_global_load_lds((const unsigned*)((const char*)(gbase) + (voff)[_i]), (LAS unsigned*)(lds + (bufoff) + ldsw + _i * 8192), 16, 0, 0); } while (0)
; #define PG8_LDA(dst, b, h) do { _Pragma("unroll") for (int m = 0; m < 4; ++m) _Pragma("unroll") for (int k = 0; k < 2; ++k) dst[m][k] = *(const LAS bf16x8*)(lds + PG8_SA(b, h) + aoff + m * 2048 + k * 1024); } while (0)
; #define PG8_LDB(dst, b, h) do { _Pragma("unroll") for (int n = 0; n < 2; ++n) _Pragma("unroll") for (int k = 0; k < 2; ++k) dst[n][k] = *(const LAS bf16x8*)(lds + PG8_SB(b, h) + boff + n * 2048 + k * 1024); } while (0)
; #define PG8_WAIT_L(n) asm volatile("s_waitcnt lgkmcnt(" #n ")" ::: "memory")
; #define PG8_BAR __builtin_amdgcn_s_barrier()
; #define PG8_SCHED __builtin_amdgcn_sched_barrier(0)
; template <class Epi, class Sched>
; DI void gemm_phase(LAS unsigned char* lds, const Gemm g, const Sched& S, const Epi& E) {
;     ...
;   unsigned voffA[2], voffB[2];
; #pragma unroll
;   for (int i = 0; i < 2; ++i) {
;     int R, C; stage_rc(tid * 16 + i * 8192, R, C);
;     int Rb = R;
;     if (Epi::BMAP == 1) Rb = (R & ~31) + perm32(R & 31);
;     if (Epi::BMAP == 2) Rb = 64 * (R >> 5) + perm32(R & 31);
;     voffA[i] = (unsigned)(R * K + C) * 2u; voffB[i] = (unsigned)(Rb * K + C) * 2u;
;   }
;   const size_t kstep = (size_t)(BK * 2);
;   const size_t hstep = (size_t)HALF * K * 2;
;   const size_t hstepB = (Epi::BMAP == 2) ? (size_t)32 * K * 2 : hstep;
;   const size_t tstep = 2 * hstep;
;   const unsigned ldsw = (unsigned)wid * 1024u;
;   const int aoff = lds_byte(wr * 64 + fr, fq * 8), boff = lds_byte(wc * 32 + fr, fq * 8);
;     ...
;     for (int t = 0; t < nt; t += 2) {
;       const bool last = (t == nt - 2);
;       const char* a1 = cA + (size_t)(t + 1) * kstep;
;       const char* a2 = last ? nA : cA + (size_t)(t + 2) * kstep; const char* b2 = last ? nB : cB + (size_t)(t + 2) * kstep;
;       const char* a3 = a2 + kstep; const char* b3 = b2 + kstep;
;       PG8_LDB(B0, 0, 0); PG8_SCHED; PG8_LDA(At, 0, 0); PG8_STAGE(PG8_SA(1, 1), a1 + hstep, voffA);
;       PG8_WAIT_L(8); PG8_BAR; PG8_WAIT_L(0); PG8_MMA(0, 0, At, B0); PG8_BAR; PG8_SCHED;
	s_lshr_b32 s18, s17, 26
	s_add_i32 s18, s16, s18
	s_ashr_i32 s38, s18, 6
	v_lshlrev_b32_e32 v2, 4, v136
	v_lshlrev_b32_e32 v3, 6, v146
	s_movk_i32 s18, 0x3c0
	v_lshlrev_b32_e32 v4, 2, v146
	v_and_or_b32 v3, v3, s18, v2
	s_lshl_b32 s18, s20, 13
	v_and_b32_e32 v4, 32, v4
	v_bitop3_b32 v3, v3, s18, v4 bitop3:0xde
	v_lshlrev_b32_e32 v4, 2, v132
	v_lshl_or_b32 v2, v132, 6, v2
	s_lshl_b32 s18, s27, 7
	v_and_b32_e32 v4, 32, v4
	v_bitop3_b32 v137, v2, s18, v4 bitop3:0xde
	s_lshl_b64 s[18:19], s[2:3], 9
	s_or_b32 s3, s18, 0x100
	s_mul_i32 s17, s3, s17
	s_mul_hi_u32 s18, s3, s16
	s_add_i32 s17, s18, s17
	s_mul_i32 s18, s19, s16
	s_add_i32 s39, s38, -2
	s_add_i32 s17, s17, s18
	s_mul_i32 s3, s3, s16
	s_add_u32 s16, s90, s3
	s_addc_u32 s17, s91, s17
	v_mov_b32_e32 v2, 0
	v_lshl_add_u64 v[132:133], s[16:17], 0, v[0:1]
	v_lshl_add_u64 v[134:135], s[16:17], 0, v[130:131]
	s_mov_b32 s3, 0
	s_mov_b64 s[16:17], 0x80
	v_add_u32_e32 v138, 16, v3
	v_mov_b32_e32 v3, v2
	v_mov_b32_e32 v4, v2
	v_mov_b32_e32 v5, v2
	v_mov_b32_e32 v6, v2
	v_mov_b32_e32 v7, v2
	v_mov_b32_e32 v8, v2
	v_mov_b32_e32 v9, v2
	v_mov_b32_e32 v18, v2
	v_mov_b32_e32 v19, v2
	v_mov_b32_e32 v20, v2
	v_mov_b32_e32 v21, v2
	v_mov_b32_e32 v22, v2
	v_mov_b32_e32 v23, v2
	v_mov_b32_e32 v24, v2
	v_mov_b32_e32 v25, v2
	v_mov_b32_e32 v30, v2
	v_mov_b32_e32 v31, v2
	v_mov_b32_e32 v32, v2
	v_mov_b32_e32 v33, v2
	v_mov_b32_e32 v38, v2
	v_mov_b32_e32 v39, v2
	v_mov_b32_e32 v40, v2
	v_mov_b32_e32 v41, v2
	v_mov_b32_e32 v46, v2
	v_mov_b32_e32 v47, v2
	v_mov_b32_e32 v48, v2
	v_mov_b32_e32 v49, v2
	v_mov_b32_e32 v54, v2
	v_mov_b32_e32 v55, v2
	v_mov_b32_e32 v56, v2
	v_mov_b32_e32 v57, v2
	v_mov_b32_e32 v10, v2
	v_mov_b32_e32 v11, v2
	v_mov_b32_e32 v12, v2
	v_mov_b32_e32 v13, v2
	v_mov_b32_e32 v14, v2
	v_mov_b32_e32 v15, v2
	v_mov_b32_e32 v16, v2
	v_mov_b32_e32 v17, v2
	v_mov_b32_e32 v26, v2
	v_mov_b32_e32 v27, v2
	v_mov_b32_e32 v28, v2
	v_mov_b32_e32 v29, v2
	v_mov_b32_e32 v34, v2
	v_mov_b32_e32 v35, v2
	v_mov_b32_e32 v36, v2
	v_mov_b32_e32 v37, v2
	v_mov_b32_e32 v42, v2
	v_mov_b32_e32 v43, v2
	v_mov_b32_e32 v44, v2
	v_mov_b32_e32 v45, v2
	v_mov_b32_e32 v50, v2
	v_mov_b32_e32 v51, v2
	v_mov_b32_e32 v52, v2
	v_mov_b32_e32 v53, v2
	v_mov_b32_e32 v58, v2
	v_mov_b32_e32 v59, v2
	v_mov_b32_e32 v60, v2
	v_mov_b32_e32 v61, v2
	v_mov_b32_e32 v62, v2
	v_mov_b32_e32 v63, v2
	v_mov_b32_e32 v64, v2
	v_mov_b32_e32 v65, v2
	v_mov_b32_e32 v66, v2
	v_mov_b32_e32 v67, v2
	v_mov_b32_e32 v68, v2
	v_mov_b32_e32 v69, v2
	v_mov_b32_e32 v70, v2
	v_mov_b32_e32 v71, v2
	v_mov_b32_e32 v72, v2
	v_mov_b32_e32 v73, v2
	v_mov_b32_e32 v82, v2
	v_mov_b32_e32 v83, v2
	v_mov_b32_e32 v84, v2
	v_mov_b32_e32 v85, v2
	v_mov_b32_e32 v86, v2
	v_mov_b32_e32 v87, v2
	v_mov_b32_e32 v88, v2
	v_mov_b32_e32 v89, v2
	v_mov_b32_e32 v98, v2
	v_mov_b32_e32 v99, v2
	v_mov_b32_e32 v100, v2
	v_mov_b32_e32 v101, v2
	v_mov_b32_e32 v102, v2
	v_mov_b32_e32 v103, v2
	v_mov_b32_e32 v104, v2
	v_mov_b32_e32 v105, v2
	v_mov_b32_e32 v114, v2
	v_mov_b32_e32 v115, v2
	v_mov_b32_e32 v116, v2
	v_mov_b32_e32 v117, v2
	v_mov_b32_e32 v118, v2
	v_mov_b32_e32 v119, v2
	v_mov_b32_e32 v120, v2
	v_mov_b32_e32 v121, v2
	v_mov_b32_e32 v74, v2
	v_mov_b32_e32 v75, v2
	v_mov_b32_e32 v76, v2
	v_mov_b32_e32 v77, v2
	v_mov_b32_e32 v78, v2
	v_mov_b32_e32 v79, v2
	v_mov_b32_e32 v80, v2
	v_mov_b32_e32 v81, v2
	v_mov_b32_e32 v90, v2
	v_mov_b32_e32 v91, v2
	v_mov_b32_e32 v92, v2
	v_mov_b32_e32 v93, v2
	v_mov_b32_e32 v94, v2
	v_mov_b32_e32 v95, v2
	v_mov_b32_e32 v96, v2
	v_mov_b32_e32 v97, v2
	v_mov_b32_e32 v106, v2
	v_mov_b32_e32 v107, v2
	v_mov_b32_e32 v108, v2
	v_mov_b32_e32 v109, v2
	v_mov_b32_e32 v110, v2
	v_mov_b32_e32 v111, v2
	v_mov_b32_e32 v112, v2
	v_mov_b32_e32 v113, v2
	v_mov_b32_e32 v122, v2
	v_mov_b32_e32 v123, v2
	v_mov_b32_e32 v124, v2
	v_mov_b32_e32 v125, v2
	v_mov_b32_e32 v126, v2
	v_mov_b32_e32 v127, v2
	v_mov_b32_e32 v128, v2
	v_mov_b32_e32 v129, v2
	v_lshrrev_b32_e32 v229, 4, v213
	v_and_b32_e32 v228, 15, v213
	v_lshlrev_b32_e32 v229, 12, v229
	v_lshl_or_b32 v229, v228, 6, v229
	s_lshl_b32 s42, s2, 20
	s_lshl_b32 s43, s26, 10
	s_add_u32 s42, s42, s43
	s_add_u32 s42, s0, s42
	s_addc_u32 s43, s1, 0
.LBB0_217:
	s_add_i32 s40, s3, 2
	s_add_u32 s18, s16, 0x80
	s_addc_u32 s19, s17, 0
	s_cmp_lg_u32 s39, s3
	s_cselect_b32 s20, s18, 0
	s_cselect_b32 s3, s19, 0
	s_add_u32 s18, s14, s20
	s_addc_u32 s19, s15, s3
	s_add_i32 s41, 16, 0x10000
	v_add_u32_e32 v139, s41, v137
	ds_read_b128 v[140:143], v139
	ds_read_b128 v[148:151], v139 offset:1024
	ds_read_b128 v[152:155], v139 offset:2048
	ds_read_b128 v[156:159], v139 offset:3072
	s_add_u32 s20, s12, s20
	s_addc_u32 s21, s13, s3
	v_lshl_add_u64 v[144:145], v[132:133], 0, s[16:17]
	s_add_i32 m0, s30, 0xc000
	ds_read_b128 v[160:163], v138
	ds_read_b128 v[164:167], v138 offset:1024
	ds_read_b128 v[168:171], v138 offset:2048
	ds_read_b128 v[172:175], v138 offset:3072
	ds_read_b128 v[186:189], v138 offset:4096
	ds_read_b128 v[190:193], v138 offset:5120
	ds_read_b128 v[198:201], v138 offset:6144
	ds_read_b128 v[202:205], v138 offset:7168
	global_load_lds_dwordx4 v[144:145], off
	v_lshl_add_u64 v[144:145], v[134:135], 0, s[16:17]
	s_add_i32 m0, s30, 0xe000
	s_nop 0
	global_load_lds_dwordx4 v[144:145], off
	s_waitcnt lgkmcnt(8)
	s_barrier
; #define PG8_STAGE(bufoff, gbase, voff) do { _Pragma("unroll") for (int _i = 0; _i < 2; ++_i) \
;     __builtin_amdgcn_global_load_lds((const unsigned*)((const char*)(gbase) + (voff)[_i]), (LAS unsigned*)(lds + (bufoff) + ldsw + _i * 8192), 16, 0, 0); } while (0)
; #define PG8_LDA(dst, b, h) do { _Pragma("unroll") for (int m = 0; m < 4; ++m) _Pragma("unroll") for (int k = 0; k < 2; ++k) dst[m][k] = *(const LAS bf16x8*)(lds + PG8_SA(b, h) + aoff + m * 2048 + k * 1024); } while (0)
; #define PG8_LDB(dst, b, h) do { _Pragma("unroll") for (int n = 0; n < 2; ++n) _Pragma("unroll") for (int k = 0; k < 2; ++k) dst[n][k] = *(const LAS bf16x8*)(lds + PG8_SB(b, h) + boff + n * 2048 + k * 1024); } while (0)
; #define PG8_MMA(ai, bj, At, Bt) do { __builtin_amdgcn_s_setprio(1); _Pragma("unroll") for (int m = 0; m < 4; ++m) _Pragma("unroll") for (int n = 0; n < 2; ++n) _Pragma("unroll") for (int k = 0; k < 2; ++k) \
;     acc[ai][bj][m][n] = __builtin_amdgcn_mfma_f32_16x16x32_bf16(Bt[n][k], At[m][k], acc[ai][bj][m][n], 0, 0, 0); __builtin_amdgcn_s_setprio(0); } while (0)
; #define PG8_WAIT_V(n) asm volatile("s_waitcnt vmcnt(" #n ")" ::: "memory")
; #define PG8_WAIT_L(n) asm volatile("s_waitcnt lgkmcnt(" #n ")" ::: "memory")
; #define PG8_BAR __builtin_amdgcn_s_barrier()
; #define PG8_SCHED __builtin_amdgcn_sched_barrier(0)
; template <class Epi, class Sched>
; DI void gemm_phase(LAS unsigned char* lds, const Gemm g, const Sched& S, const Epi& E) {
;     ...
;       PG8_WAIT_L(8); PG8_BAR; PG8_WAIT_L(0); PG8_MMA(0, 0, At, B0); PG8_BAR; PG8_SCHED;
;       PG8_LDB(B1, 0, 1); PG8_STAGE(PG8_SB(0, 0), b2, voffB);
;       PG8_BAR; PG8_WAIT_L(0); PG8_MMA(0, 1, At, B1); PG8_BAR;
;       PG8_LDA(At, 0, 1); PG8_STAGE(PG8_SA(0, 0), a2, voffA);
;       PG8_BAR; PG8_WAIT_L(0); PG8_MMA(1, 0, At, B0); PG8_BAR; PG8_SCHED;
;       PG8_STAGE(PG8_SB(0, 1), b2 + hstepB, voffB);
;       PG8_WAIT_V(6); PG8_BAR; PG8_MMA(1, 1, At, B1); PG8_BAR;
	s_waitcnt lgkmcnt(0)
	s_setprio 1
	s_waitcnt lgkmcnt(0)
	v_mfma_f32_16x16x32_bf16 v[126:129], v[140:143], v[160:163], v[126:129]
	v_mfma_f32_16x16x32_bf16 v[122:125], v[152:155], v[160:163], v[122:125]
	v_mfma_f32_16x16x32_bf16 v[110:113], v[140:143], v[168:171], v[110:113]
	v_mfma_f32_16x16x32_bf16 v[106:109], v[152:155], v[168:171], v[106:109]
	v_mfma_f32_16x16x32_bf16 v[94:97], v[140:143], v[186:189], v[94:97]
	v_mfma_f32_16x16x32_bf16 v[90:93], v[152:155], v[186:189], v[90:93]
	v_mfma_f32_16x16x32_bf16 v[78:81], v[140:143], v[198:201], v[78:81]
	v_mfma_f32_16x16x32_bf16 v[74:77], v[152:155], v[198:201], v[74:77]
	v_mfma_f32_16x16x32_bf16 v[126:129], v[148:151], v[164:167], v[126:129]
	v_mfma_f32_16x16x32_bf16 v[122:125], v[156:159], v[164:167], v[122:125]
	v_mfma_f32_16x16x32_bf16 v[110:113], v[148:151], v[172:175], v[110:113]
	v_mfma_f32_16x16x32_bf16 v[106:109], v[156:159], v[172:175], v[106:109]
	v_mfma_f32_16x16x32_bf16 v[94:97], v[148:151], v[190:193], v[94:97]
	v_mfma_f32_16x16x32_bf16 v[90:93], v[156:159], v[190:193], v[90:93]
	v_mfma_f32_16x16x32_bf16 v[78:81], v[148:151], v[202:205], v[78:81]
	v_mfma_f32_16x16x32_bf16 v[74:77], v[156:159], v[202:205], v[74:77]
	s_setprio 0
	s_barrier
	s_add_i32 s3, 16, 0x14000
	s_add_i32 s41, s41, s29
	v_add_u32_e32 v139, s3, v137
	v_lshl_add_u64 v[144:145], s[20:21], 0, v[0:1]
	s_mov_b32 m0, s41
	ds_read_b128 v[206:209], v139
	ds_read_b128 v[214:217], v139 offset:1024
	ds_read_b128 v[218:221], v139 offset:2048
	ds_read_b128 v[222:225], v139 offset:3072
	global_load_lds_dwordx4 v[144:145], off
	v_lshl_add_u64 v[176:177], s[20:21], 0, v[130:131]
	s_add_i32 m0, s41, 0x2000
	s_nop 0
	global_load_lds_dwordx4 v[176:177], off
	s_barrier
	s_waitcnt lgkmcnt(0)
	s_setprio 1
	s_waitcnt lgkmcnt(0)
	v_mfma_f32_16x16x32_bf16 v[118:121], v[206:209], v[160:163], v[118:121]
	v_mfma_f32_16x16x32_bf16 v[114:117], v[218:221], v[160:163], v[114:117]
	v_mfma_f32_16x16x32_bf16 v[102:105], v[206:209], v[168:171], v[102:105]
	v_mfma_f32_16x16x32_bf16 v[98:101], v[218:221], v[168:171], v[98:101]
	v_mfma_f32_16x16x32_bf16 v[86:89], v[206:209], v[186:189], v[86:89]
	v_mfma_f32_16x16x32_bf16 v[82:85], v[218:221], v[186:189], v[82:85]
	v_mfma_f32_16x16x32_bf16 v[70:73], v[206:209], v[198:201], v[70:73]
	v_mfma_f32_16x16x32_bf16 v[66:69], v[218:221], v[198:201], v[66:69]
	v_mfma_f32_16x16x32_bf16 v[118:121], v[214:217], v[164:167], v[118:121]
	v_mfma_f32_16x16x32_bf16 v[114:117], v[222:225], v[164:167], v[114:117]
	v_mfma_f32_16x16x32_bf16 v[102:105], v[214:217], v[172:175], v[102:105]
	v_mfma_f32_16x16x32_bf16 v[98:101], v[222:225], v[172:175], v[98:101]
	v_mfma_f32_16x16x32_bf16 v[86:89], v[214:217], v[190:193], v[86:89]
	v_mfma_f32_16x16x32_bf16 v[82:85], v[222:225], v[190:193], v[82:85]
	v_mfma_f32_16x16x32_bf16 v[70:73], v[214:217], v[202:205], v[70:73]
	v_mfma_f32_16x16x32_bf16 v[66:69], v[222:225], v[202:205], v[66:69]
	s_setprio 0
	s_mov_b32 m0, s30
	v_lshl_add_u64 v[180:181], s[18:19], 0, v[0:1]
	s_barrier
	ds_read_b128 v[160:163], v138 offset:16384
	ds_read_b128 v[164:167], v138 offset:17408
	ds_read_b128 v[168:171], v138 offset:18432
	ds_read_b128 v[172:175], v138 offset:19456
	ds_read_b128 v[186:189], v138 offset:20480
	ds_read_b128 v[190:193], v138 offset:21504
	ds_read_b128 v[198:201], v138 offset:22528
	ds_read_b128 v[202:205], v138 offset:23552
	global_load_lds_dwordx4 v[180:181], off
	v_lshl_add_u64 v[182:183], s[18:19], 0, v[130:131]
	s_mov_b32 m0, s31
	s_nop 0
	global_load_lds_dwordx4 v[182:183], off
	s_barrier
	s_waitcnt lgkmcnt(0)
	s_setprio 1
	s_waitcnt lgkmcnt(0)
	v_mfma_f32_16x16x32_bf16 v[62:65], v[140:143], v[160:163], v[62:65]
	v_mfma_f32_16x16x32_bf16 v[58:61], v[152:155], v[160:163], v[58:61]
	v_mfma_f32_16x16x32_bf16 v[50:53], v[140:143], v[168:171], v[50:53]
	v_mfma_f32_16x16x32_bf16 v[42:45], v[152:155], v[168:171], v[42:45]
	v_mfma_f32_16x16x32_bf16 v[34:37], v[140:143], v[186:189], v[34:37]
	v_mfma_f32_16x16x32_bf16 v[26:29], v[152:155], v[186:189], v[26:29]
	v_mfma_f32_16x16x32_bf16 v[14:17], v[140:143], v[198:201], v[14:17]
	v_mfma_f32_16x16x32_bf16 v[10:13], v[152:155], v[198:201], v[10:13]
	v_mfma_f32_16x16x32_bf16 v[62:65], v[148:151], v[164:167], v[62:65]
	v_mfma_f32_16x16x32_bf16 v[58:61], v[156:159], v[164:167], v[58:61]
	v_mfma_f32_16x16x32_bf16 v[50:53], v[148:151], v[172:175], v[50:53]
	v_mfma_f32_16x16x32_bf16 v[42:45], v[156:159], v[172:175], v[42:45]
	v_mfma_f32_16x16x32_bf16 v[34:37], v[148:151], v[190:193], v[34:37]
	v_mfma_f32_16x16x32_bf16 v[26:29], v[156:159], v[190:193], v[26:29]
	v_mfma_f32_16x16x32_bf16 v[14:17], v[148:151], v[202:205], v[14:17]
	v_mfma_f32_16x16x32_bf16 v[10:13], v[156:159], v[202:205], v[10:13]
	s_setprio 0
	s_barrier
	s_add_u32 s20, s20, s10
	s_addc_u32 s21, s21, s11
	s_add_i32 s3, s3, s29
	v_lshl_add_u64 v[184:185], s[20:21], 0, v[0:1]
	s_mov_b32 m0, s3
	v_lshl_add_u64 v[226:227], s[20:21], 0, v[130:131]
	global_load_lds_dwordx4 v[184:185], off
	s_add_i32 m0, s3, 0x2000
	s_nop 0
	global_load_lds_dwordx4 v[226:227], off
	global_load_dword v228, v229, s[42:43]
	s_add_u32 s42, s42, 0x20000
	s_addc_u32 s43, s43, 0
	s_waitcnt vmcnt(7)
	s_barrier
; #define PG8_STAGE(bufoff, gbase, voff) do { _Pragma("unroll") for (int _i = 0; _i < 2; ++_i) \
;     __builtin_amdgcn_global_load_lds((const unsigned*)((const char*)(gbase) + (voff)[_i]), (LAS unsigned*)(lds + (bufoff) + ldsw + _i * 8192), 16, 0, 0); } while (0)
; #define PG8_LDA(dst, b, h) do { _Pragma("unroll") for (int m = 0; m < 4; ++m) _Pragma("unroll") for (int k = 0; k < 2; ++k) dst[m][k] = *(const LAS bf16x8*)(lds + PG8_SA(b, h) + aoff + m * 2048 + k * 1024); } while (0)
; #define PG8_LDB(dst, b, h) do { _Pragma("unroll") for (int n = 0; n < 2; ++n) _Pragma("unroll") for (int k = 0; k < 2; ++k) dst[n][k] = *(const LAS bf16x8*)(lds + PG8_SB(b, h) + boff + n * 2048 + k * 1024); } while (0)
; #define PG8_MMA(ai, bj, At, Bt) do { __builtin_amdgcn_s_setprio(1); _Pragma("unroll") for (int m = 0; m < 4; ++m) _Pragma("unroll") for (int n = 0; n < 2; ++n) _Pragma("unroll") for (int k = 0; k < 2; ++k) \
;     acc[ai][bj][m][n] = __builtin_amdgcn_mfma_f32_16x16x32_bf16(Bt[n][k], At[m][k], acc[ai][bj][m][n], 0, 0, 0); __builtin_amdgcn_s_setprio(0); } while (0)
; #define PG8_WAIT_V(n) asm volatile("s_waitcnt vmcnt(" #n ")" ::: "memory")
; #define PG8_WAIT_L(n) asm volatile("s_waitcnt lgkmcnt(" #n ")" ::: "memory")
; #define PG8_BAR __builtin_amdgcn_s_barrier()
; #define PG8_SCHED __builtin_amdgcn_sched_barrier(0)
; template <class Epi, class Sched>
; DI void gemm_phase(LAS unsigned char* lds, const Gemm g, const Sched& S, const Epi& E) {
;     ...
;       PG8_WAIT_V(6); PG8_BAR; PG8_MMA(1, 1, At, B1); PG8_BAR;
;       PG8_LDB(B0, 1, 0); PG8_SCHED; PG8_LDA(At, 1, 0); PG8_STAGE(PG8_SA(0, 1), a2 + hstep, voffA);
;       PG8_WAIT_L(8); PG8_BAR; PG8_WAIT_L(0); PG8_MMA(0, 0, At, B0); PG8_BAR; PG8_SCHED;
;       PG8_LDB(B1, 1, 1); PG8_STAGE(PG8_SB(1, 0), b3, voffB);
	s_setprio 1
	v_mfma_f32_16x16x32_bf16 v[54:57], v[206:209], v[160:163], v[54:57]
	v_mfma_f32_16x16x32_bf16 v[46:49], v[218:221], v[160:163], v[46:49]
	v_mfma_f32_16x16x32_bf16 v[38:41], v[206:209], v[168:171], v[38:41]
	v_mfma_f32_16x16x32_bf16 v[30:33], v[218:221], v[168:171], v[30:33]
	v_mfma_f32_16x16x32_bf16 v[22:25], v[206:209], v[186:189], v[22:25]
	v_mfma_f32_16x16x32_bf16 v[18:21], v[218:221], v[186:189], v[18:21]
	v_mfma_f32_16x16x32_bf16 v[6:9], v[206:209], v[198:201], v[6:9]
	v_mfma_f32_16x16x32_bf16 v[2:5], v[218:221], v[198:201], v[2:5]
	v_mfma_f32_16x16x32_bf16 v[54:57], v[214:217], v[164:167], v[54:57]
	v_mfma_f32_16x16x32_bf16 v[46:49], v[222:225], v[164:167], v[46:49]
	v_mfma_f32_16x16x32_bf16 v[38:41], v[214:217], v[172:175], v[38:41]
	v_mfma_f32_16x16x32_bf16 v[30:33], v[222:225], v[172:175], v[30:33]
	v_mfma_f32_16x16x32_bf16 v[22:25], v[214:217], v[190:193], v[22:25]
	v_mfma_f32_16x16x32_bf16 v[18:21], v[222:225], v[190:193], v[18:21]
	v_mfma_f32_16x16x32_bf16 v[6:9], v[214:217], v[202:205], v[6:9]
	v_mfma_f32_16x16x32_bf16 v[2:5], v[222:225], v[202:205], v[2:5]
	s_setprio 0
	s_add_i32 s3, 16, 0x18000
	v_add_u32_e32 v139, s3, v137
	s_barrier
	ds_read_b128 v[140:143], v139
	ds_read_b128 v[148:151], v139 offset:1024
	ds_read_b128 v[152:155], v139 offset:2048
	ds_read_b128 v[156:159], v139 offset:3072
	s_add_u32 s18, s18, s10
	s_addc_u32 s19, s19, s11
	s_mov_b32 m0, s34
	v_lshl_add_u64 v[206:207], s[18:19], 0, v[0:1]
	ds_read_b128 v[160:163], v138 offset:32768
	ds_read_b128 v[164:167], v138 offset:33792
	ds_read_b128 v[168:171], v138 offset:34816
	ds_read_b128 v[172:175], v138 offset:35840
	ds_read_b128 v[186:189], v138 offset:36864
	ds_read_b128 v[190:193], v138 offset:37888
	ds_read_b128 v[198:201], v138 offset:38912
	ds_read_b128 v[202:205], v138 offset:39936
	global_load_lds_dwordx4 v[206:207], off
	v_lshl_add_u64 v[206:207], s[18:19], 0, v[130:131]
	s_mov_b32 m0, s35
	s_nop 0
	global_load_lds_dwordx4 v[206:207], off
	s_waitcnt lgkmcnt(8)
	s_barrier
	s_waitcnt lgkmcnt(0)
	s_setprio 1
	s_waitcnt lgkmcnt(0)
	v_mfma_f32_16x16x32_bf16 v[126:129], v[140:143], v[160:163], v[126:129]
	v_mfma_f32_16x16x32_bf16 v[122:125], v[152:155], v[160:163], v[122:125]
	v_mfma_f32_16x16x32_bf16 v[110:113], v[140:143], v[168:171], v[110:113]
	v_mfma_f32_16x16x32_bf16 v[106:109], v[152:155], v[168:171], v[106:109]
	v_mfma_f32_16x16x32_bf16 v[94:97], v[140:143], v[186:189], v[94:97]
	v_mfma_f32_16x16x32_bf16 v[90:93], v[152:155], v[186:189], v[90:93]
	v_mfma_f32_16x16x32_bf16 v[78:81], v[140:143], v[198:201], v[78:81]
	v_mfma_f32_16x16x32_bf16 v[74:77], v[152:155], v[198:201], v[74:77]
	v_mfma_f32_16x16x32_bf16 v[126:129], v[148:151], v[164:167], v[126:129]
	v_mfma_f32_16x16x32_bf16 v[122:125], v[156:159], v[164:167], v[122:125]
	v_mfma_f32_16x16x32_bf16 v[110:113], v[148:151], v[172:175], v[110:113]
	v_mfma_f32_16x16x32_bf16 v[106:109], v[156:159], v[172:175], v[106:109]
	v_mfma_f32_16x16x32_bf16 v[94:97], v[148:151], v[190:193], v[94:97]
	v_mfma_f32_16x16x32_bf16 v[90:93], v[156:159], v[190:193], v[90:93]
	v_mfma_f32_16x16x32_bf16 v[78:81], v[148:151], v[202:205], v[78:81]
	v_mfma_f32_16x16x32_bf16 v[74:77], v[156:159], v[202:205], v[74:77]
	s_setprio 0
	s_barrier
	s_add_i32 s18, 16, 0x1c000
	s_add_i32 s3, s3, s29
	v_add_u32_e32 v139, s18, v137
	v_lshl_add_u64 v[144:145], v[144:145], 0, s[70:71]
	s_mov_b32 m0, s3
	ds_read_b128 v[206:209], v139
	ds_read_b128 v[214:217], v139 offset:1024
	ds_read_b128 v[218:221], v139 offset:2048
	ds_read_b128 v[222:225], v139 offset:3072
	global_load_lds_dwordx4 v[144:145], off
	v_lshl_add_u64 v[144:145], v[176:177], 0, s[70:71]
	s_add_i32 m0, s3, 0x2000
	s_nop 0
	global_load_lds_dwordx4 v[144:145], off
	s_barrier
; #define PG8_STAGE(bufoff, gbase, voff) do { _Pragma("unroll") for (int _i = 0; _i < 2; ++_i) \
;     __builtin_amdgcn_global_load_lds((const unsigned*)((const char*)(gbase) + (voff)[_i]), (LAS unsigned*)(lds + (bufoff) + ldsw + _i * 8192), 16, 0, 0); } while (0)
; #define PG8_LDA(dst, b, h) do { _Pragma("unroll") for (int m = 0; m < 4; ++m) _Pragma("unroll") for (int k = 0; k < 2; ++k) dst[m][k] = *(const LAS bf16x8*)(lds + PG8_SA(b, h) + aoff + m * 2048 + k * 1024); } while (0)
; #define PG8_MMA(ai, bj, At, Bt) do { __builtin_amdgcn_s_setprio(1); _Pragma("unroll") for (int m = 0; m < 4; ++m) _Pragma("unroll") for (int n = 0; n < 2; ++n) _Pragma("unroll") for (int k = 0; k < 2; ++k) \
;     acc[ai][bj][m][n] = __builtin_amdgcn_mfma_f32_16x16x32_bf16(Bt[n][k], At[m][k], acc[ai][bj][m][n], 0, 0, 0); __builtin_amdgcn_s_setprio(0); } while (0)
; #define PG8_WAIT_V(n) asm volatile("s_waitcnt vmcnt(" #n ")" ::: "memory")
; #define PG8_WAIT_L(n) asm volatile("s_waitcnt lgkmcnt(" #n ")" ::: "memory")
; #define PG8_BAR __builtin_amdgcn_s_barrier()
; #define PG8_SCHED __builtin_amdgcn_sched_barrier(0)
; template <class Epi, class Sched>
; DI void gemm_phase(LAS unsigned char* lds, const Gemm g, const Sched& S, const Epi& E) {
;     ...
;       PG8_BAR; PG8_WAIT_L(0); PG8_MMA(0, 1, At, B1); PG8_BAR;
;       PG8_LDA(At, 1, 1); PG8_STAGE(PG8_SA(1, 0), a3, voffA);
;       PG8_BAR; PG8_WAIT_L(0); PG8_MMA(1, 0, At, B0); PG8_BAR; PG8_SCHED;
;       PG8_STAGE(PG8_SB(1, 1), b3 + hstepB, voffB);
;       PG8_WAIT_V(6); PG8_BAR; PG8_MMA(1, 1, At, B1); PG8_BAR;
	s_waitcnt lgkmcnt(0)
	s_setprio 1
	s_waitcnt lgkmcnt(0)
	v_mfma_f32_16x16x32_bf16 v[118:121], v[206:209], v[160:163], v[118:121]
	v_mfma_f32_16x16x32_bf16 v[114:117], v[218:221], v[160:163], v[114:117]
	v_mfma_f32_16x16x32_bf16 v[102:105], v[206:209], v[168:171], v[102:105]
	v_mfma_f32_16x16x32_bf16 v[98:101], v[218:221], v[168:171], v[98:101]
	v_mfma_f32_16x16x32_bf16 v[86:89], v[206:209], v[186:189], v[86:89]
	v_mfma_f32_16x16x32_bf16 v[82:85], v[218:221], v[186:189], v[82:85]
	v_mfma_f32_16x16x32_bf16 v[70:73], v[206:209], v[198:201], v[70:73]
	v_mfma_f32_16x16x32_bf16 v[66:69], v[218:221], v[198:201], v[66:69]
	v_mfma_f32_16x16x32_bf16 v[118:121], v[214:217], v[164:167], v[118:121]
	v_mfma_f32_16x16x32_bf16 v[114:117], v[222:225], v[164:167], v[114:117]
	v_mfma_f32_16x16x32_bf16 v[102:105], v[214:217], v[172:175], v[102:105]
	v_mfma_f32_16x16x32_bf16 v[98:101], v[222:225], v[172:175], v[98:101]
	v_mfma_f32_16x16x32_bf16 v[86:89], v[214:217], v[190:193], v[86:89]
	v_mfma_f32_16x16x32_bf16 v[82:85], v[222:225], v[190:193], v[82:85]
	v_mfma_f32_16x16x32_bf16 v[70:73], v[214:217], v[202:205], v[70:73]
	v_mfma_f32_16x16x32_bf16 v[66:69], v[222:225], v[202:205], v[66:69]
	s_setprio 0
	s_mov_b32 m0, s36
	v_lshl_add_u64 v[144:145], v[180:181], 0, s[70:71]
	s_barrier
	ds_read_b128 v[160:163], v138 offset:49152
	ds_read_b128 v[164:167], v138 offset:50176
	ds_read_b128 v[168:171], v138 offset:51200
	ds_read_b128 v[172:175], v138 offset:52224
	ds_read_b128 v[186:189], v138 offset:53248
	ds_read_b128 v[190:193], v138 offset:54272
	ds_read_b128 v[198:201], v138 offset:55296
	ds_read_b128 v[202:205], v138 offset:56320
	global_load_lds_dwordx4 v[144:145], off
	v_lshl_add_u64 v[144:145], v[182:183], 0, s[70:71]
	s_mov_b32 m0, s37
	s_nop 0
	global_load_lds_dwordx4 v[144:145], off
	s_barrier
	s_waitcnt lgkmcnt(0)
	s_setprio 1
	s_waitcnt lgkmcnt(0)
	v_mfma_f32_16x16x32_bf16 v[62:65], v[140:143], v[160:163], v[62:65]
	v_mfma_f32_16x16x32_bf16 v[58:61], v[152:155], v[160:163], v[58:61]
	v_mfma_f32_16x16x32_bf16 v[50:53], v[140:143], v[168:171], v[50:53]
	v_mfma_f32_16x16x32_bf16 v[42:45], v[152:155], v[168:171], v[42:45]
	v_mfma_f32_16x16x32_bf16 v[34:37], v[140:143], v[186:189], v[34:37]
	v_mfma_f32_16x16x32_bf16 v[26:29], v[152:155], v[186:189], v[26:29]
	v_mfma_f32_16x16x32_bf16 v[14:17], v[140:143], v[198:201], v[14:17]
	v_mfma_f32_16x16x32_bf16 v[10:13], v[152:155], v[198:201], v[10:13]
	v_mfma_f32_16x16x32_bf16 v[62:65], v[148:151], v[164:167], v[62:65]
	v_mfma_f32_16x16x32_bf16 v[58:61], v[156:159], v[164:167], v[58:61]
	v_mfma_f32_16x16x32_bf16 v[50:53], v[148:151], v[172:175], v[50:53]
	v_mfma_f32_16x16x32_bf16 v[42:45], v[156:159], v[172:175], v[42:45]
	v_mfma_f32_16x16x32_bf16 v[34:37], v[148:151], v[190:193], v[34:37]
	v_mfma_f32_16x16x32_bf16 v[26:29], v[156:159], v[190:193], v[26:29]
	v_mfma_f32_16x16x32_bf16 v[14:17], v[148:151], v[202:205], v[14:17]
	v_mfma_f32_16x16x32_bf16 v[10:13], v[156:159], v[202:205], v[10:13]
	s_setprio 0
	s_barrier
	s_add_i32 s3, s18, s29
	v_lshl_add_u64 v[140:141], v[184:185], 0, s[70:71]
	s_mov_b32 m0, s3
	s_nop 0
	global_load_lds_dwordx4 v[140:141], off
	v_lshl_add_u64 v[140:141], v[226:227], 0, s[70:71]
	s_add_i32 m0, s3, 0x2000
	s_nop 0
	global_load_lds_dwordx4 v[140:141], off
	s_waitcnt vmcnt(6)
	s_barrier
	s_setprio 1
	v_mfma_f32_16x16x32_bf16 v[54:57], v[206:209], v[160:163], v[54:57]
	v_mfma_f32_16x16x32_bf16 v[46:49], v[218:221], v[160:163], v[46:49]
	v_mfma_f32_16x16x32_bf16 v[38:41], v[206:209], v[168:171], v[38:41]
	v_mfma_f32_16x16x32_bf16 v[30:33], v[218:221], v[168:171], v[30:33]
	v_mfma_f32_16x16x32_bf16 v[22:25], v[206:209], v[186:189], v[22:25]
	v_mfma_f32_16x16x32_bf16 v[18:21], v[218:221], v[186:189], v[18:21]
	v_mfma_f32_16x16x32_bf16 v[6:9], v[206:209], v[198:201], v[6:9]
	v_mfma_f32_16x16x32_bf16 v[2:5], v[218:221], v[198:201], v[2:5]
	v_mfma_f32_16x16x32_bf16 v[54:57], v[214:217], v[164:167], v[54:57]
	v_mfma_f32_16x16x32_bf16 v[46:49], v[222:225], v[164:167], v[46:49]
	v_mfma_f32_16x16x32_bf16 v[38:41], v[214:217], v[172:175], v[38:41]
	v_mfma_f32_16x16x32_bf16 v[30:33], v[222:225], v[172:175], v[30:33]
	v_mfma_f32_16x16x32_bf16 v[22:25], v[214:217], v[190:193], v[22:25]
	v_mfma_f32_16x16x32_bf16 v[18:21], v[222:225], v[190:193], v[18:21]
	v_mfma_f32_16x16x32_bf16 v[6:9], v[214:217], v[202:205], v[6:9]
	v_mfma_f32_16x16x32_bf16 v[2:5], v[222:225], v[202:205], v[2:5]
	s_setprio 0
	s_add_u32 s16, s16, 0x100
	s_addc_u32 s17, s17, 0
	s_cmp_ge_i32 s40, s38
	s_mov_b32 s3, s40
	s_barrier
	s_cbranch_scc0 .LBB0_217
